# in-projection: column-tile index relabelled tn -> (5 tn + 19) mod 22 so the tiles with heavy epilogues (q, k, gated conv) are spread evenly over the six-tile workgroups
# speedup vs baseline: 1.0092x; 1.0037x over previous
.LBB0_241:
	s_andn2_b64 vcc, exec, s[0:1]
	s_cbranch_vccnz .LBB0_243
	s_and_b32 s0, s58, 0xffff
	s_mul_i32 s0, s0, 0xba2f
	s_lshr_b32 s0, s0, 23
	s_mul_i32 s1, s0, 0xb0
	s_sub_i32 s1, s58, s1
	s_bfe_u32 s42, s1, 0xd0003
	s_lshl_b32 s0, s0, 3
	s_and_b32 s1, s1, 7
	s_or_b32 s18, s1, s0
	s_mul_i32 s0, s42, 5
	s_add_i32 s0, s0, 19
	s_mul_i32 s1, s0, 0xba3
	s_lshr_b32 s1, s1, 16
	s_mul_i32 s1, s1, 22
	s_sub_i32 s42, s0, s1
